# P0 weight conversion rewritten by hand: one item loop, LDS-DMA 16B loads into padded LDS image, double-buffered across items
# baseline (speedup 1.0000x reference)
; __device__ __forceinline__ void p0_prologue(KP P, LAS unsigned char* lds, int G) {
;     const int tid = opaque_tid(), lane = tid & 63, wid = __builtin_amdgcn_readfirstlane(tid >> 6);
;     LAS float* scr = (LAS float*)(lds + wid * 16384);
;     const int gw = blockIdx.x * NWAVES + wid, NGW = G * NWAVES;
;     constexpr int I_AIN = 16 * 96, I_AO = 16 * 32, I_GIN = 16 * 96, I_GO = 16 * 32, I_UP = 16 * 128, I_DN = 64 * 32;
;     constexpr int NITEMS = 2 * I_AIN + 2 * I_AO + 2 * I_GIN + 2 * I_GO + 4 * I_UP + 4 * I_DN;
;     for (int it = gw; it < NITEMS; it += NGW) {
;         int r = it;
;         if (r < 2 * I_AIN) { const int j = r / I_AIN; r -= j * I_AIN; const int kb = r / 96, nb = r % 96;
;             p0_transpose_item(P->attn_w_in + (size_t)j * 1024 * 3072, 3072, 1024, (bf16_t*)(P->ws + WS_WQKV + j * WS_WQKV_STRIDE), 64 * kb, 32 * nb, 32 * nb, scr, lane); continue; }
;         r -= 2 * I_AIN;
;         if (r < 2 * I_AO) { const int j = r / I_AO; r -= j * I_AO; const int kb = r / 32, nb = r % 32;
;             p0_transpose_item(P->attn_w_out + (size_t)j * 1024 * 1024, 1024, 1024, (bf16_t*)(P->ws + WS_WAO + j * WS_WAO_STRIDE), 64 * kb, 32 * nb, 32 * nb, scr, lane); continue; }
;         r -= 2 * I_AO;
;         if (r < 2 * I_GIN) { const int j = r / I_GIN; r -= j * I_GIN; const int kb = r / 96, nb = r % 96; const int n0 = 32 * nb;
;             const int orow = n0 < 1024 ? n0 : (n0 < 2048 ? n0 + 1024 : n0 - 1024);
;             p0_transpose_item(P->gla_w_in + (size_t)j * 1024 * 3088, 3088, 1024, (bf16_t*)(P->ws + WS_WGLA + j * WS_WGLA_STRIDE), 64 * kb, n0, orow, scr, lane); continue; }
;         r -= 2 * I_GIN;
;         if (r < 2 * I_GO) { const int j = r / I_GO; r -= j * I_GO; const int kb = r / 32, nb = r % 32;
;             p0_transpose_item(P->gla_w_out + (size_t)j * 1024 * 1024, 1024, 1024, (bf16_t*)(P->ws + WS_WGO + j * WS_WGO_STRIDE), 64 * kb, 32 * nb, 32 * nb, scr, lane); continue; }
;         r -= 2 * I_GO;
;         if (r < 4 * I_UP) { const int j = r / I_UP; r -= j * I_UP; const int kb = r / 128, nb = r % 128;
;             p0_transpose_item(P->mlp_up + (size_t)j * 1024 * 4096, 4096, 1024, (bf16_t*)(P->ws + WS_WUP + j * WS_WUP_STRIDE), 64 * kb, 32 * nb, 32 * nb, scr, lane); continue; }
;         r -= 4 * I_UP;
;         { const int j = r / I_DN; r -= j * I_DN; const int kb = r / 32, nb = r % 32;
.LBB0_5:
	s_or_b64 exec, exec, s[0:1]
	s_mov_b64 s[0:1], s[90:91]
	v_mov_b32_e32 v3, v194
	s_lshl_b32 s88, s94, 3
	v_readfirstlane_b32 s2, v3
	s_ashr_i32 s3, s2, 6
	s_lshl_b32 s2, s92, 3
	v_writelane_b32 v253, s2, 4
	s_add_i32 s2, s3, s2
	s_cmpk_gt_i32 s2, 0x5fff
	s_cbranch_scc1 .LBB0_40
	s_load_dwordx2 s[30:31], s[0:1], 0x18
	s_load_dwordx2 s[32:33], s[0:1], 0x30
	s_load_dwordx2 s[34:35], s[0:1], 0x38
	s_load_dwordx2 s[36:37], s[0:1], 0x58
	s_load_dwordx2 s[38:39], s[0:1], 0x68
	s_load_dwordx2 s[40:41], s[0:1], 0x70
	s_load_dwordx2 s[42:43], s[0:1], 0x88
	v_and_b32_e32 v54, 63, v3
	s_mul_i32 s4, s3, 0x4400
	v_and_b32_e32 v55, 7, v54
	v_lshrrev_b32_e32 v56, 3, v54
	v_mul_u32_u24_e32 v57, 0x410, v55
	v_lshlrev_b32_e32 v58, 4, v55
	v_lshl_add_u32 v57, v56, 2, v57
	v_add_u32_e32 v57, s4, v57
	v_add_u32_e32 v61, 0x2080, v57
	s_mov_b32 s44, 0
	s_waitcnt lgkmcnt(0)
	s_mov_b32 s6, s2
	s_cmp_lt_u32 s6, 3072
	s_cbranch_scc0 .Lp0_dec_a0_1
	s_cmp_ge_u32 s6, 1536
	s_cselect_b32 s7, 1, 0
	s_cselect_b32 s20, 1536, 0
	s_sub_u32 s6, s6, s20
	s_mul_i32 s20, s6, 683
	s_lshr_b32 s20, s20, 16
	s_mul_i32 s21, s20, 96
	s_sub_u32 s21, s6, s21
	s_lshl_b32 s20, s20, 6
	s_lshl_b32 s21, s21, 5
	s_mul_i32 s22, s7, 12582912
	s_mul_i32 s23, s20, 3072
	s_add_u32 s23, s23, s21
	s_lshl_b32 s23, s23, 2
	s_add_u32 s22, s22, s23
	s_add_u32 s8, s30, s22
	s_addc_u32 s9, s31, 0
	s_mov_b32 s10, 12288
	s_mul_i32 s22, s21, 1024
	s_add_u32 s22, s22, s20
	s_lshl_b32 s22, s22, 1
	s_mul_i32 s23, s7, 6291456
	s_add_u32 s22, s22, s23
	s_add_u32 s22, s22, 1048576
	s_add_u32 s12, s42, s22
	s_addc_u32 s13, s43, 0
	s_mov_b32 s14, 2048
	s_branch .Lp0_dec_a0_done
.Lp0_dec_a0_1:
	s_sub_u32 s6, s6, 3072
	s_cmp_lt_u32 s6, 1024
	s_cbranch_scc0 .Lp0_dec_a0_2
	s_cmp_ge_u32 s6, 512
	s_cselect_b32 s7, 1, 0
	s_cselect_b32 s20, 512, 0
	s_sub_u32 s6, s6, s20
	s_lshr_b32 s20, s6, 5
	s_and_b32 s21, s6, 31
	s_lshl_b32 s20, s20, 6
	s_lshl_b32 s21, s21, 5
	s_mul_i32 s22, s7, 4194304
	s_mul_i32 s23, s20, 1024
	s_add_u32 s23, s23, s21
	s_lshl_b32 s23, s23, 2
	s_add_u32 s22, s22, s23
	s_add_u32 s8, s32, s22
	s_addc_u32 s9, s33, 0
	s_mov_b32 s10, 4096
	s_mul_i32 s22, s21, 1024
	s_add_u32 s22, s22, s20
	s_lshl_b32 s22, s22, 1
	s_mul_i32 s23, s7, 2097152
	s_add_u32 s22, s22, s23
	s_add_u32 s22, s22, 13631488
	s_add_u32 s12, s42, s22
	s_addc_u32 s13, s43, 0
	s_mov_b32 s14, 2048
	s_branch .Lp0_dec_a0_done
.Lp0_dec_a0_2:
	s_sub_u32 s6, s6, 1024
	s_cmp_lt_u32 s6, 3072
	s_cbranch_scc0 .Lp0_dec_a0_3
	s_cmp_ge_u32 s6, 1536
	s_cselect_b32 s7, 1, 0
	s_cselect_b32 s20, 1536, 0
	s_sub_u32 s6, s6, s20
	s_mul_i32 s20, s6, 683
	s_lshr_b32 s20, s20, 16
	s_mul_i32 s21, s20, 96
	s_sub_u32 s21, s6, s21
	s_lshl_b32 s20, s20, 6
	s_lshl_b32 s21, s21, 5
	s_mul_i32 s22, s7, 12648448
	s_mul_i32 s23, s20, 3088
	s_add_u32 s23, s23, s21
	s_lshl_b32 s23, s23, 2
	s_add_u32 s22, s22, s23
	s_add_u32 s8, s34, s22
	s_addc_u32 s9, s35, 0
	s_mov_b32 s10, 12352
	s_add_u32 s22, s21, 0x400
	s_sub_u32 s23, s21, 0x400
	s_cmp_lt_u32 s21, 0x800
	s_cselect_b32 s22, s22, s23
	s_cmp_lt_u32 s21, 0x400
	s_cselect_b32 s21, s21, s22
	s_mul_i32 s22, s21, 1024
	s_add_u32 s22, s22, s20
	s_lshl_b32 s22, s22, 1
	s_mul_i32 s23, s7, 7340032
	s_add_u32 s22, s22, s23
	s_add_u32 s22, s22, 17825792
	s_add_u32 s12, s42, s22
	s_addc_u32 s13, s43, 0
	s_mov_b32 s14, 2048
	s_branch .Lp0_dec_a0_done
.Lp0_dec_a0_3:
	s_sub_u32 s6, s6, 3072
	s_cmp_lt_u32 s6, 1024
	s_cbranch_scc0 .Lp0_dec_a0_4
	s_cmp_ge_u32 s6, 512
	s_cselect_b32 s7, 1, 0
	s_cselect_b32 s20, 512, 0
	s_sub_u32 s6, s6, s20
	s_lshr_b32 s20, s6, 5
	s_and_b32 s21, s6, 31
	s_lshl_b32 s20, s20, 6
	s_lshl_b32 s21, s21, 5
	s_mul_i32 s22, s7, 4194304
	s_mul_i32 s23, s20, 1024
	s_add_u32 s23, s23, s21
	s_lshl_b32 s23, s23, 2
	s_add_u32 s22, s22, s23
	s_add_u32 s8, s36, s22
	s_addc_u32 s9, s37, 0
	s_mov_b32 s10, 4096
	s_mul_i32 s22, s21, 1024
	s_add_u32 s22, s22, s20
	s_lshl_b32 s22, s22, 1
	s_mul_i32 s23, s7, 2097152
	s_add_u32 s22, s22, s23
	s_add_u32 s22, s22, 32505856
	s_add_u32 s12, s42, s22
	s_addc_u32 s13, s43, 0
	s_mov_b32 s14, 2048
	s_branch .Lp0_dec_a0_done
.Lp0_dec_a0_4:
	s_sub_u32 s6, s6, 1024
	s_cmp_lt_u32 s6, 8192
	s_cbranch_scc0 .Lp0_dec_a0_5
	s_lshr_b32 s7, s6, 11
	s_and_b32 s6, s6, 0x7ff
	s_lshr_b32 s20, s6, 7
	s_and_b32 s21, s6, 127
	s_lshl_b32 s20, s20, 6
	s_lshl_b32 s21, s21, 5
	s_mul_i32 s22, s7, 16777216
	s_mul_i32 s23, s20, 4096
	s_add_u32 s23, s23, s21
	s_lshl_b32 s23, s23, 2
	s_add_u32 s22, s22, s23
	s_add_u32 s8, s38, s22
	s_addc_u32 s9, s39, 0
	s_mov_b32 s10, 16384
	s_mul_i32 s22, s21, 1024
	s_add_u32 s22, s22, s20
	s_lshl_b32 s22, s22, 1
	s_mul_i32 s23, s7, 8388608
	s_add_u32 s22, s22, s23
	s_add_u32 s22, s22, 36700160
	s_add_u32 s12, s42, s22
	s_addc_u32 s13, s43, 0
	s_mov_b32 s14, 2048
	s_branch .Lp0_dec_a0_done
.Lp0_dec_a0_5:
	s_sub_u32 s6, s6, 8192
	s_lshr_b32 s7, s6, 11
	s_and_b32 s6, s6, 0x7ff
	s_lshr_b32 s20, s6, 5
	s_and_b32 s21, s6, 31
	s_lshl_b32 s20, s20, 6
	s_lshl_b32 s21, s21, 5
	s_mul_i32 s22, s7, 16777216
	s_mul_i32 s23, s20, 1024
	s_add_u32 s23, s23, s21
	s_lshl_b32 s23, s23, 2
	s_add_u32 s22, s22, s23
	s_add_u32 s8, s40, s22
	s_addc_u32 s9, s41, 0
	s_mov_b32 s10, 4096
	s_mul_i32 s22, s21, 4096
	s_add_u32 s22, s22, s20
	s_lshl_b32 s22, s22, 1
	s_mul_i32 s23, s7, 8388608
	s_add_u32 s22, s22, s23
	s_add_u32 s22, s22, 70254592
	s_add_u32 s12, s42, s22
	s_addc_u32 s13, s43, 0
	s_mov_b32 s14, 8192
	s_branch .Lp0_dec_a0_done
; #define LAS __attribute__((address_space(3)))
; __device__ __forceinline__ void p0_transpose_item(const float* W, int ldw, int K, bf16_t* WT, int k0, int n0, int orow0, LAS float* scr, int lane) {
; #pragma unroll 8
;     for (int i = 0; i < 32; ++i) { const int kk = 2 * i + (lane >> 5); scr[kk * 33 + (lane & 31)] = W[(size_t)(k0 + kk) * ldw + n0 + (lane & 31)]; }
; __device__ __forceinline__ void p0_prologue(KP P, LAS unsigned char* lds, int G) {
;     ...
;     for (int it = gw; it < NITEMS; it += NGW) {
;         int r = it;
;         if (r < 2 * I_AIN) { const int j = r / I_AIN; r -= j * I_AIN; const int kb = r / 96, nb = r % 96;
;             p0_transpose_item(P->attn_w_in + (size_t)j * 1024 * 3072, 3072, 1024, (bf16_t*)(P->ws + WS_WQKV + j * WS_WQKV_STRIDE), 64 * kb, 32 * nb, 32 * nb, scr, lane); continue; }
;         r -= 2 * I_AIN;
;         if (r < 2 * I_AO) { const int j = r / I_AO; r -= j * I_AO; const int kb = r / 32, nb = r % 32;
;             p0_transpose_item(P->attn_w_out + (size_t)j * 1024 * 1024, 1024, 1024, (bf16_t*)(P->ws + WS_WAO + j * WS_WAO_STRIDE), 64 * kb, 32 * nb, 32 * nb, scr, lane); continue; }
;         r -= 2 * I_AO;
;         if (r < 2 * I_GIN) { const int j = r / I_GIN; r -= j * I_GIN; const int kb = r / 96, nb = r % 96; const int n0 = 32 * nb;
;             const int orow = n0 < 1024 ? n0 : (n0 < 2048 ? n0 + 1024 : n0 - 1024);
;             p0_transpose_item(P->gla_w_in + (size_t)j * 1024 * 3088, 3088, 1024, (bf16_t*)(P->ws + WS_WGLA + j * WS_WGLA_STRIDE), 64 * kb, n0, orow, scr, lane); continue; }
;         r -= 2 * I_GIN;
;         if (r < 2 * I_GO) { const int j = r / I_GO; r -= j * I_GO; const int kb = r / 32, nb = r % 32;
;             p0_transpose_item(P->gla_w_out + (size_t)j * 1024 * 1024, 1024, 1024, (bf16_t*)(P->ws + WS_WGO + j * WS_WGO_STRIDE), 64 * kb, 32 * nb, 32 * nb, scr, lane); continue; }
;         r -= 2 * I_GO;
;         if (r < 4 * I_UP) { const int j = r / I_UP; r -= j * I_UP; const int kb = r / 128, nb = r % 128;
;             p0_transpose_item(P->mlp_up + (size_t)j * 1024 * 4096, 4096, 1024, (bf16_t*)(P->ws + WS_WUP + j * WS_WUP_STRIDE), 64 * kb, 32 * nb, 32 * nb, scr, lane); continue; }
;         r -= 4 * I_UP;
;         { const int j = r / I_DN; r -= j * I_DN; const int kb = r / 32, nb = r % 32;
.Lp0_dec_a0_done:
	v_mad_u32_u24 v60, v56, s10, v58
	s_lshl_b32 s11, s10, 3
	s_add_i32 s19, s4, 0
	s_mov_b32 m0, s19
	s_add_i32 s19, s19, 1040
	global_load_lds_dwordx4 v60, s[8:9]
	s_add_u32 s8, s8, s11
	s_addc_u32 s9, s9, 0
	s_mov_b32 m0, s19
	s_add_i32 s19, s19, 1040
	global_load_lds_dwordx4 v60, s[8:9]
	s_add_u32 s8, s8, s11
	s_addc_u32 s9, s9, 0
	s_mov_b32 m0, s19
	s_add_i32 s19, s19, 1040
	global_load_lds_dwordx4 v60, s[8:9]
	s_add_u32 s8, s8, s11
	s_addc_u32 s9, s9, 0
	s_mov_b32 m0, s19
	s_add_i32 s19, s19, 1040
	global_load_lds_dwordx4 v60, s[8:9]
	s_add_u32 s8, s8, s11
	s_addc_u32 s9, s9, 0
	s_mov_b32 m0, s19
	s_add_i32 s19, s19, 1040
	global_load_lds_dwordx4 v60, s[8:9]
	s_add_u32 s8, s8, s11
	s_addc_u32 s9, s9, 0
	s_mov_b32 m0, s19
	s_add_i32 s19, s19, 1040
	global_load_lds_dwordx4 v60, s[8:9]
	s_add_u32 s8, s8, s11
	s_addc_u32 s9, s9, 0
	s_mov_b32 m0, s19
	s_add_i32 s19, s19, 1040
	global_load_lds_dwordx4 v60, s[8:9]
	s_add_u32 s8, s8, s11
	s_addc_u32 s9, s9, 0
	s_mov_b32 m0, s19
	s_add_i32 s19, s19, 1040
	global_load_lds_dwordx4 v60, s[8:9]
	s_add_i32 s2, s2, s88
.Lp0_loop:
	s_cmp_lt_u32 s2, 24576
	s_cbranch_scc0 .Lp0_lastA
	s_mov_b32 s6, s2
	s_cmp_lt_u32 s6, 3072
	s_cbranch_scc0 .Lp0_dec_b_1
	s_cmp_ge_u32 s6, 1536
	s_cselect_b32 s7, 1, 0
	s_cselect_b32 s20, 1536, 0
	s_sub_u32 s6, s6, s20
	s_mul_i32 s20, s6, 683
	s_lshr_b32 s20, s20, 16
	s_mul_i32 s21, s20, 96
	s_sub_u32 s21, s6, s21
	s_lshl_b32 s20, s20, 6
	s_lshl_b32 s21, s21, 5
	s_mul_i32 s22, s7, 12582912
	s_mul_i32 s23, s20, 3072
	s_add_u32 s23, s23, s21
	s_lshl_b32 s23, s23, 2
	s_add_u32 s22, s22, s23
	s_add_u32 s8, s30, s22
	s_addc_u32 s9, s31, 0
	s_mov_b32 s10, 12288
	s_mul_i32 s22, s21, 1024
	s_add_u32 s22, s22, s20
	s_lshl_b32 s22, s22, 1
	s_mul_i32 s23, s7, 6291456
	s_add_u32 s22, s22, s23
	s_add_u32 s22, s22, 1048576
	s_add_u32 s16, s42, s22
	s_addc_u32 s17, s43, 0
	s_mov_b32 s18, 2048
	s_branch .Lp0_dec_b_done
.Lp0_dec_b_1:
	s_sub_u32 s6, s6, 3072
	s_cmp_lt_u32 s6, 1024
	s_cbranch_scc0 .Lp0_dec_b_2
	s_cmp_ge_u32 s6, 512
	s_cselect_b32 s7, 1, 0
	s_cselect_b32 s20, 512, 0
	s_sub_u32 s6, s6, s20
	s_lshr_b32 s20, s6, 5
	s_and_b32 s21, s6, 31
	s_lshl_b32 s20, s20, 6
	s_lshl_b32 s21, s21, 5
	s_mul_i32 s22, s7, 4194304
	s_mul_i32 s23, s20, 1024
	s_add_u32 s23, s23, s21
	s_lshl_b32 s23, s23, 2
	s_add_u32 s22, s22, s23
	s_add_u32 s8, s32, s22
	s_addc_u32 s9, s33, 0
	s_mov_b32 s10, 4096
	s_mul_i32 s22, s21, 1024
	s_add_u32 s22, s22, s20
	s_lshl_b32 s22, s22, 1
	s_mul_i32 s23, s7, 2097152
	s_add_u32 s22, s22, s23
	s_add_u32 s22, s22, 13631488
	s_add_u32 s16, s42, s22
	s_addc_u32 s17, s43, 0
	s_mov_b32 s18, 2048
	s_branch .Lp0_dec_b_done
.Lp0_dec_b_2:
	s_sub_u32 s6, s6, 1024
	s_cmp_lt_u32 s6, 3072
	s_cbranch_scc0 .Lp0_dec_b_3
	s_cmp_ge_u32 s6, 1536
	s_cselect_b32 s7, 1, 0
	s_cselect_b32 s20, 1536, 0
	s_sub_u32 s6, s6, s20
	s_mul_i32 s20, s6, 683
	s_lshr_b32 s20, s20, 16
	s_mul_i32 s21, s20, 96
	s_sub_u32 s21, s6, s21
	s_lshl_b32 s20, s20, 6
	s_lshl_b32 s21, s21, 5
	s_mul_i32 s22, s7, 12648448
	s_mul_i32 s23, s20, 3088
	s_add_u32 s23, s23, s21
	s_lshl_b32 s23, s23, 2
	s_add_u32 s22, s22, s23
	s_add_u32 s8, s34, s22
	s_addc_u32 s9, s35, 0
	s_mov_b32 s10, 12352
	s_add_u32 s22, s21, 0x400
	s_sub_u32 s23, s21, 0x400
	s_cmp_lt_u32 s21, 0x800
	s_cselect_b32 s22, s22, s23
	s_cmp_lt_u32 s21, 0x400
	s_cselect_b32 s21, s21, s22
	s_mul_i32 s22, s21, 1024
	s_add_u32 s22, s22, s20
	s_lshl_b32 s22, s22, 1
	s_mul_i32 s23, s7, 7340032
	s_add_u32 s22, s22, s23
	s_add_u32 s22, s22, 17825792
	s_add_u32 s16, s42, s22
	s_addc_u32 s17, s43, 0
	s_mov_b32 s18, 2048
	s_branch .Lp0_dec_b_done
.Lp0_dec_b_3:
	s_sub_u32 s6, s6, 3072
	s_cmp_lt_u32 s6, 1024
	s_cbranch_scc0 .Lp0_dec_b_4
	s_cmp_ge_u32 s6, 512
	s_cselect_b32 s7, 1, 0
	s_cselect_b32 s20, 512, 0
	s_sub_u32 s6, s6, s20
	s_lshr_b32 s20, s6, 5
	s_and_b32 s21, s6, 31
	s_lshl_b32 s20, s20, 6
	s_lshl_b32 s21, s21, 5
	s_mul_i32 s22, s7, 4194304
	s_mul_i32 s23, s20, 1024
	s_add_u32 s23, s23, s21
	s_lshl_b32 s23, s23, 2
	s_add_u32 s22, s22, s23
	s_add_u32 s8, s36, s22
	s_addc_u32 s9, s37, 0
	s_mov_b32 s10, 4096
	s_mul_i32 s22, s21, 1024
	s_add_u32 s22, s22, s20
	s_lshl_b32 s22, s22, 1
	s_mul_i32 s23, s7, 2097152
	s_add_u32 s22, s22, s23
	s_add_u32 s22, s22, 32505856
	s_add_u32 s16, s42, s22
	s_addc_u32 s17, s43, 0
	s_mov_b32 s18, 2048
	s_branch .Lp0_dec_b_done
.Lp0_dec_b_4:
	s_sub_u32 s6, s6, 1024
	s_cmp_lt_u32 s6, 8192
	s_cbranch_scc0 .Lp0_dec_b_5
	s_lshr_b32 s7, s6, 11
	s_and_b32 s6, s6, 0x7ff
	s_lshr_b32 s20, s6, 7
	s_and_b32 s21, s6, 127
	s_lshl_b32 s20, s20, 6
	s_lshl_b32 s21, s21, 5
	s_mul_i32 s22, s7, 16777216
	s_mul_i32 s23, s20, 4096
	s_add_u32 s23, s23, s21
	s_lshl_b32 s23, s23, 2
	s_add_u32 s22, s22, s23
	s_add_u32 s8, s38, s22
	s_addc_u32 s9, s39, 0
	s_mov_b32 s10, 16384
	s_mul_i32 s22, s21, 1024
	s_add_u32 s22, s22, s20
	s_lshl_b32 s22, s22, 1
	s_mul_i32 s23, s7, 8388608
	s_add_u32 s22, s22, s23
	s_add_u32 s22, s22, 36700160
	s_add_u32 s16, s42, s22
	s_addc_u32 s17, s43, 0
	s_mov_b32 s18, 2048
	s_branch .Lp0_dec_b_done
; #define LAS __attribute__((address_space(3)))
; __device__ __forceinline__ unsigned pk_bf16(float lo, float hi) { f32x2_t v = {lo, hi}; bf16x2_t b = __builtin_convertvector(v, bf16x2_t); return __builtin_bit_cast(unsigned, b); }
; __device__ __forceinline__ void p0_transpose_item(const float* W, int ldw, int K, bf16_t* WT, int k0, int n0, int orow0, LAS float* scr, int lane) {
;     ...
;     for (int i = 0; i < 32; ++i) { const int kk = 2 * i + (lane >> 5); scr[kk * 33 + (lane & 31)] = W[(size_t)(k0 + kk) * ldw + n0 + (lane & 31)]; }
;     asm volatile("s_waitcnt lgkmcnt(0)" ::: "memory");
;     const int c = lane & 7;
; #pragma unroll
;     for (int j = 0; j < 4; ++j) { const int n = (lane >> 3) + 8 * j; const LAS float* s = scr + (8 * c) * 33 + n;
;         u32x4 o; o.x = pk_bf16(s[0 * 33], s[1 * 33]); o.y = pk_bf16(s[2 * 33], s[3 * 33]); o.z = pk_bf16(s[4 * 33], s[5 * 33]); o.w = pk_bf16(s[6 * 33], s[7 * 33]);
;         *(u32x4*)(WT + (size_t)(orow0 + n) * K + k0 + 8 * c) = o; }
; __device__ __forceinline__ void p0_prologue(KP P, LAS unsigned char* lds, int G) {
;     ...
;         if (r < 4 * I_UP) { const int j = r / I_UP; r -= j * I_UP; const int kb = r / 128, nb = r % 128;
;             p0_transpose_item(P->mlp_up + (size_t)j * 1024 * 4096, 4096, 1024, (bf16_t*)(P->ws + WS_WUP + j * WS_WUP_STRIDE), 64 * kb, 32 * nb, 32 * nb, scr, lane); continue; }
;         r -= 4 * I_UP;
;         { const int j = r / I_DN; r -= j * I_DN; const int kb = r / 32, nb = r % 32;
;             p0_transpose_item(P->mlp_dn + (size_t)j * 4096 * 1024, 1024, 4096, (bf16_t*)(P->ws + WS_WDN + j * WS_WDN_STRIDE), 64 * kb, 32 * nb, 32 * nb, scr, lane); }
.Lp0_dec_b_5:
	s_sub_u32 s6, s6, 8192
	s_lshr_b32 s7, s6, 11
	s_and_b32 s6, s6, 0x7ff
	s_lshr_b32 s20, s6, 5
	s_and_b32 s21, s6, 31
	s_lshl_b32 s20, s20, 6
	s_lshl_b32 s21, s21, 5
	s_mul_i32 s22, s7, 16777216
	s_mul_i32 s23, s20, 1024
	s_add_u32 s23, s23, s21
	s_lshl_b32 s23, s23, 2
	s_add_u32 s22, s22, s23
	s_add_u32 s8, s40, s22
	s_addc_u32 s9, s41, 0
	s_mov_b32 s10, 4096
	s_mul_i32 s22, s21, 4096
	s_add_u32 s22, s22, s20
	s_lshl_b32 s22, s22, 1
	s_mul_i32 s23, s7, 8388608
	s_add_u32 s22, s22, s23
	s_add_u32 s22, s22, 70254592
	s_add_u32 s16, s42, s22
	s_addc_u32 s17, s43, 0
	s_mov_b32 s18, 8192
	s_branch .Lp0_dec_b_done
.Lp0_dec_b_done:
	v_mad_u32_u24 v60, v56, s10, v58
	s_lshl_b32 s11, s10, 3
	s_add_i32 s19, s4, 8320
	s_mov_b32 m0, s19
	s_add_i32 s19, s19, 1040
	global_load_lds_dwordx4 v60, s[8:9]
	s_add_u32 s8, s8, s11
	s_addc_u32 s9, s9, 0
	s_mov_b32 m0, s19
	s_add_i32 s19, s19, 1040
	global_load_lds_dwordx4 v60, s[8:9]
	s_add_u32 s8, s8, s11
	s_addc_u32 s9, s9, 0
	s_mov_b32 m0, s19
	s_add_i32 s19, s19, 1040
	global_load_lds_dwordx4 v60, s[8:9]
	s_add_u32 s8, s8, s11
	s_addc_u32 s9, s9, 0
	s_mov_b32 m0, s19
	s_add_i32 s19, s19, 1040
	global_load_lds_dwordx4 v60, s[8:9]
	s_add_u32 s8, s8, s11
	s_addc_u32 s9, s9, 0
	s_mov_b32 m0, s19
	s_add_i32 s19, s19, 1040
	global_load_lds_dwordx4 v60, s[8:9]
	s_add_u32 s8, s8, s11
	s_addc_u32 s9, s9, 0
	s_mov_b32 m0, s19
	s_add_i32 s19, s19, 1040
	global_load_lds_dwordx4 v60, s[8:9]
	s_add_u32 s8, s8, s11
	s_addc_u32 s9, s9, 0
	s_mov_b32 m0, s19
	s_add_i32 s19, s19, 1040
	global_load_lds_dwordx4 v60, s[8:9]
	s_add_u32 s8, s8, s11
	s_addc_u32 s9, s9, 0
	s_mov_b32 m0, s19
	s_add_i32 s19, s19, 1040
	global_load_lds_dwordx4 v60, s[8:9]
	s_add_i32 s2, s2, s88
	s_waitcnt vmcnt(8)
.Lp0_consA:
	ds_read2_b32 v[64:65], v57 offset0:0 offset1:32
	ds_read2_b32 v[66:67], v57 offset0:64 offset1:96
	ds_read2_b32 v[68:69], v57 offset0:128 offset1:160
	ds_read2_b32 v[70:71], v57 offset0:192 offset1:224
	ds_read2_b32 v[72:73], v57 offset0:8 offset1:40
	ds_read2_b32 v[74:75], v57 offset0:72 offset1:104
	ds_read2_b32 v[76:77], v57 offset0:136 offset1:168
	ds_read2_b32 v[78:79], v57 offset0:200 offset1:232
	ds_read2_b32 v[80:81], v57 offset0:16 offset1:48
	ds_read2_b32 v[82:83], v57 offset0:80 offset1:112
	ds_read2_b32 v[84:85], v57 offset0:144 offset1:176
	ds_read2_b32 v[86:87], v57 offset0:208 offset1:240
	ds_read2_b32 v[88:89], v57 offset0:24 offset1:56
	ds_read2_b32 v[90:91], v57 offset0:88 offset1:120
	ds_read2_b32 v[92:93], v57 offset0:152 offset1:184
	ds_read2_b32 v[94:95], v57 offset0:216 offset1:248
	s_waitcnt lgkmcnt(0)
	v_mad_u32_u24 v59, v56, s14, v58
	s_lshl_b32 s6, s14, 3
	v_cvt_pk_bf16_f32 v96, v64, v65
	v_cvt_pk_bf16_f32 v97, v66, v67
	v_cvt_pk_bf16_f32 v98, v68, v69
	v_cvt_pk_bf16_f32 v99, v70, v71
	global_store_dwordx4 v59, v[96:99], s[12:13]
	s_add_u32 s12, s12, s6
	s_addc_u32 s13, s13, 0
	s_nop 0
	v_cvt_pk_bf16_f32 v96, v72, v73
	v_cvt_pk_bf16_f32 v97, v74, v75
	v_cvt_pk_bf16_f32 v98, v76, v77
	v_cvt_pk_bf16_f32 v99, v78, v79
	global_store_dwordx4 v59, v[96:99], s[12:13]
	s_add_u32 s12, s12, s6
	s_addc_u32 s13, s13, 0
	s_nop 0
	v_cvt_pk_bf16_f32 v96, v80, v81
	v_cvt_pk_bf16_f32 v97, v82, v83
	v_cvt_pk_bf16_f32 v98, v84, v85
	v_cvt_pk_bf16_f32 v99, v86, v87
	global_store_dwordx4 v59, v[96:99], s[12:13]
	s_add_u32 s12, s12, s6
	s_addc_u32 s13, s13, 0
	s_nop 0
	v_cvt_pk_bf16_f32 v96, v88, v89
	v_cvt_pk_bf16_f32 v97, v90, v91
	v_cvt_pk_bf16_f32 v98, v92, v93
	v_cvt_pk_bf16_f32 v99, v94, v95
	global_store_dwordx4 v59, v[96:99], s[12:13]
	s_cmp_lg_u32 s44, 0
	s_cbranch_scc1 .LBB0_40
	s_cmp_lt_u32 s2, 24576
	s_cbranch_scc0 .Lp0_lastB
	s_mov_b32 s6, s2
	s_cmp_lt_u32 s6, 3072
	s_cbranch_scc0 .Lp0_dec_a_1
	s_cmp_ge_u32 s6, 1536
	s_cselect_b32 s7, 1, 0
	s_cselect_b32 s20, 1536, 0
	s_sub_u32 s6, s6, s20
	s_mul_i32 s20, s6, 683
	s_lshr_b32 s20, s20, 16
	s_mul_i32 s21, s20, 96
	s_sub_u32 s21, s6, s21
	s_lshl_b32 s20, s20, 6
	s_lshl_b32 s21, s21, 5
	s_mul_i32 s22, s7, 12582912
	s_mul_i32 s23, s20, 3072
	s_add_u32 s23, s23, s21
	s_lshl_b32 s23, s23, 2
	s_add_u32 s22, s22, s23
	s_add_u32 s8, s30, s22
	s_addc_u32 s9, s31, 0
	s_mov_b32 s10, 12288
	s_mul_i32 s22, s21, 1024
	s_add_u32 s22, s22, s20
	s_lshl_b32 s22, s22, 1
	s_mul_i32 s23, s7, 6291456
	s_add_u32 s22, s22, s23
	s_add_u32 s22, s22, 1048576
	s_add_u32 s12, s42, s22
	s_addc_u32 s13, s43, 0
	s_mov_b32 s14, 2048
	s_branch .Lp0_dec_a_done

; #define LAS __attribute__((address_space(3)))
; __device__ __forceinline__ unsigned pk_bf16(float lo, float hi) { f32x2_t v = {lo, hi}; bf16x2_t b = __builtin_convertvector(v, bf16x2_t); return __builtin_bit_cast(unsigned, b); }
; __device__ __forceinline__ void p0_transpose_item(const float* W, int ldw, int K, bf16_t* WT, int k0, int n0, int orow0, LAS float* scr, int lane) {
; #pragma unroll 8
;     for (int i = 0; i < 32; ++i) { const int kk = 2 * i + (lane >> 5); scr[kk * 33 + (lane & 31)] = W[(size_t)(k0 + kk) * ldw + n0 + (lane & 31)]; }
;     asm volatile("s_waitcnt lgkmcnt(0)" ::: "memory");
;     const int c = lane & 7;
; #pragma unroll
;     for (int j = 0; j < 4; ++j) { const int n = (lane >> 3) + 8 * j; const LAS float* s = scr + (8 * c) * 33 + n;
;         u32x4 o; o.x = pk_bf16(s[0 * 33], s[1 * 33]); o.y = pk_bf16(s[2 * 33], s[3 * 33]); o.z = pk_bf16(s[4 * 33], s[5 * 33]); o.w = pk_bf16(s[6 * 33], s[7 * 33]);
;         *(u32x4*)(WT + (size_t)(orow0 + n) * K + k0 + 8 * c) = o; }
;     asm volatile("s_waitcnt lgkmcnt(0)" ::: "memory");
; }
.Lp0_dec_a_done:
	v_mad_u32_u24 v60, v56, s10, v58
	s_lshl_b32 s11, s10, 3
	s_add_i32 s19, s4, 0
	s_mov_b32 m0, s19
	s_add_i32 s19, s19, 1040
	global_load_lds_dwordx4 v60, s[8:9]
	s_add_u32 s8, s8, s11
	s_addc_u32 s9, s9, 0
	s_mov_b32 m0, s19
	s_add_i32 s19, s19, 1040
	global_load_lds_dwordx4 v60, s[8:9]
	s_add_u32 s8, s8, s11
	s_addc_u32 s9, s9, 0
	s_mov_b32 m0, s19
	s_add_i32 s19, s19, 1040
	global_load_lds_dwordx4 v60, s[8:9]
	s_add_u32 s8, s8, s11
	s_addc_u32 s9, s9, 0
	s_mov_b32 m0, s19
	s_add_i32 s19, s19, 1040
	global_load_lds_dwordx4 v60, s[8:9]
	s_add_u32 s8, s8, s11
	s_addc_u32 s9, s9, 0
	s_mov_b32 m0, s19
	s_add_i32 s19, s19, 1040
	global_load_lds_dwordx4 v60, s[8:9]
	s_add_u32 s8, s8, s11
	s_addc_u32 s9, s9, 0
	s_mov_b32 m0, s19
	s_add_i32 s19, s19, 1040
	global_load_lds_dwordx4 v60, s[8:9]
	s_add_u32 s8, s8, s11
	s_addc_u32 s9, s9, 0
	s_mov_b32 m0, s19
	s_add_i32 s19, s19, 1040
	global_load_lds_dwordx4 v60, s[8:9]
	s_add_u32 s8, s8, s11
	s_addc_u32 s9, s9, 0
	s_mov_b32 m0, s19
	s_add_i32 s19, s19, 1040
	global_load_lds_dwordx4 v60, s[8:9]
	s_add_i32 s2, s2, s88
	s_waitcnt vmcnt(8)
.Lp0_consB:
	ds_read2_b32 v[64:65], v61 offset0:0 offset1:32
	ds_read2_b32 v[66:67], v61 offset0:64 offset1:96
	ds_read2_b32 v[68:69], v61 offset0:128 offset1:160
	ds_read2_b32 v[70:71], v61 offset0:192 offset1:224
	ds_read2_b32 v[72:73], v61 offset0:8 offset1:40
	ds_read2_b32 v[74:75], v61 offset0:72 offset1:104
	ds_read2_b32 v[76:77], v61 offset0:136 offset1:168
	ds_read2_b32 v[78:79], v61 offset0:200 offset1:232
	ds_read2_b32 v[80:81], v61 offset0:16 offset1:48
	ds_read2_b32 v[82:83], v61 offset0:80 offset1:112
	ds_read2_b32 v[84:85], v61 offset0:144 offset1:176
	ds_read2_b32 v[86:87], v61 offset0:208 offset1:240
	ds_read2_b32 v[88:89], v61 offset0:24 offset1:56
	ds_read2_b32 v[90:91], v61 offset0:88 offset1:120
	ds_read2_b32 v[92:93], v61 offset0:152 offset1:184
	ds_read2_b32 v[94:95], v61 offset0:216 offset1:248
	s_waitcnt lgkmcnt(0)
	v_mad_u32_u24 v59, v56, s18, v58
	s_lshl_b32 s6, s18, 3
	v_cvt_pk_bf16_f32 v96, v64, v65
	v_cvt_pk_bf16_f32 v97, v66, v67
	v_cvt_pk_bf16_f32 v98, v68, v69
	v_cvt_pk_bf16_f32 v99, v70, v71
	global_store_dwordx4 v59, v[96:99], s[16:17]
	s_add_u32 s16, s16, s6
	s_addc_u32 s17, s17, 0
	s_nop 0
	v_cvt_pk_bf16_f32 v96, v72, v73
	v_cvt_pk_bf16_f32 v97, v74, v75
	v_cvt_pk_bf16_f32 v98, v76, v77
	v_cvt_pk_bf16_f32 v99, v78, v79
	global_store_dwordx4 v59, v[96:99], s[16:17]
	s_add_u32 s16, s16, s6
	s_addc_u32 s17, s17, 0
	s_nop 0
	v_cvt_pk_bf16_f32 v96, v80, v81
	v_cvt_pk_bf16_f32 v97, v82, v83
	v_cvt_pk_bf16_f32 v98, v84, v85
	v_cvt_pk_bf16_f32 v99, v86, v87
	global_store_dwordx4 v59, v[96:99], s[16:17]
	s_add_u32 s16, s16, s6
	s_addc_u32 s17, s17, 0
	s_nop 0
	v_cvt_pk_bf16_f32 v96, v88, v89
	v_cvt_pk_bf16_f32 v97, v90, v91
	v_cvt_pk_bf16_f32 v98, v92, v93
	v_cvt_pk_bf16_f32 v99, v94, v95
	global_store_dwordx4 v59, v[96:99], s[16:17]
	s_cmp_lg_u32 s44, 0
	s_cbranch_scc1 .LBB0_40
	s_branch .Lp0_loop
.Lp0_lastA:
	s_mov_b32 s44, 1
	s_waitcnt vmcnt(0)
	s_branch .Lp0_consA
